# v60 + s_setprio hand-off in scan steps 3-5: waves 4-7 lead at prio 1 until the kk=0 state update, then prio 0
# speedup vs baseline: 1.0030x; 1.0030x over previous
.LBB0_380:
	s_or_b64 exec, exec, s[94:95]
	s_add_i32 s14, s15, 1
	s_cmp_lt_u32 s14, s0
	s_cselect_b32 s15, s14, s15
	s_lshl_b32 s16, s15, 6
	s_add_i32 s16, s16, s97
	s_cmp_eq_u32 s15, 0
	s_cselect_b32 s15, 0, 0x1000
	s_waitcnt lgkmcnt(0)
	s_barrier
	s_waitcnt vmcnt(0)
	ds_write_b128 v230, v[136:139]
	ds_write_b128 v230, v[140:143] offset:128
	ds_write_b128 v230, v[144:147] offset:256
	ds_write_b128 v230, v[148:151] offset:384
	v_readlane_b32 s98, v254, 52
	v_readlane_b32 s99, v254, 53
	v_readfirstlane_b32 s100, v1
	s_nop 3
	v_subrev_u32_e32 v151, s98, v176
	s_cmp_lg_u32 s100, 0
	s_cselect_b32 s101, 0x1000, s15
	s_add_i32 s100, s100, s16
	s_lshl_b32 s100, s100, 13
	s_add_u32 s98, s98, s100
	s_addc_u32 s99, s99, 0
	s_mul_i32 s100, s101, 6
	s_sub_u32 s98, s98, s100
	s_subb_u32 s99, s99, 0
	s_lshl_b32 s100, s101, 1
	v_add_u32_e32 v2, s16, v159
	v_ashrrev_i32_e32 v3, 31, v2
	v_lshlrev_b64 v[2:3], 7, v[2:3]
	v_lshl_add_u64 v[2:3], s[90:91], 0, v[2:3]
	global_load_dword v153, v[2:3], off
	ds_read_b128 v[84:87], v180
	ds_read_b128 v[88:91], v181 offset:17408
	ds_read_b128 v[92:95], v181 offset:21760
	global_load_dword v250, v151, s[98:99]
	ds_read_b128 v[68:71], v180 offset:64
	ds_read_b128 v[96:99], v181 offset:17472
	ds_read_b128 v[100:103], v181 offset:21824
	ds_read_b128 v[72:75], v180 offset:128
	ds_read_b128 v[76:79], v181 offset:17536
	v_add_u32_e32 v192, v178, v228
	ds_read_b128 v[80:83], v181 offset:21888
	ds_read_b128 v[104:107], v180 offset:192
	s_waitcnt lgkmcnt(8)
	v_mfma_f32_16x16x32_bf16 v[88:91], v[84:87], v[88:91], 0
	s_add_u32 s98, s98, s100
	s_addc_u32 s99, s99, 0
	global_load_dword v251, v151, s[98:99]
	ds_read_b128 v[108:111], v181 offset:17600
	s_waitcnt lgkmcnt(8)
	v_mfma_f32_16x16x32_bf16 v[84:87], v[84:87], v[92:95], 0
	ds_read_b128 v[112:115], v181 offset:21952
	s_waitcnt lgkmcnt(7)
	v_mfma_f32_16x16x32_bf16 v[88:91], v[68:71], v[96:99], v[88:91]
	s_waitcnt lgkmcnt(6)
	v_mfma_f32_16x16x32_bf16 v[84:87], v[68:71], v[100:103], v[84:87]
	s_waitcnt lgkmcnt(4)
	v_mfma_f32_16x16x32_bf16 v[88:91], v[72:75], v[76:79], v[88:91]
	s_add_u32 s98, s98, s100
	s_addc_u32 s99, s99, 0
	global_load_dword v252, v151, s[98:99]
	s_waitcnt lgkmcnt(3)
	v_mfma_f32_16x16x32_bf16 v[84:87], v[72:75], v[80:83], v[84:87]
	s_waitcnt lgkmcnt(1)
	v_mfma_f32_16x16x32_bf16 v[88:91], v[104:107], v[108:111], v[88:91]
	s_waitcnt lgkmcnt(0)
	v_mfma_f32_16x16x32_bf16 v[84:87], v[104:107], v[112:115], v[84:87]
	s_nop 7
	ds_write2_b32 v202, v88, v84 offset1:16
	ds_write2_b32 v202, v89, v85 offset0:68 offset1:84
	ds_write2_b32 v202, v90, v86 offset0:136 offset1:152
	s_add_u32 s98, s98, s100
	s_addc_u32 s99, s99, 0
	global_load_dword v249, v151, s[98:99]
	ds_write2_b32 v202, v91, v87 offset0:204 offset1:220
	ds_read2_b64 v[92:95], v224 offset1:4
	ds_read2_b64 v[100:103], v225 offset1:4
	ds_read2_b64 v[108:111], v226 offset1:4
	ds_read2_b64 v[116:119], v227 offset1:4
	ds_read2_b64 v[124:127], v224 offset0:8 offset1:12
	ds_read2_b64 v[68:71], v225 offset0:8 offset1:12
	ds_read2_b64 v[72:75], v226 offset0:8 offset1:12
	ds_read2_b64 v[76:79], v227 offset0:8 offset1:12
	v_cvt_pk_bf16_f32 v84, v4, v5
	s_add_u32 s98, s98, 0x2000
	s_addc_u32 s99, s99, 0
	global_load_dword v248, v151, s[98:99]
	v_cvt_pk_bf16_f32 v85, v6, v7
	v_cvt_pk_bf16_f32 v86, v12, v13
	v_cvt_pk_bf16_f32 v87, v14, v15
	v_cvt_pk_bf16_f32 v88, v8, v9
	v_cvt_pk_bf16_f32 v89, v10, v11
	v_cvt_pk_bf16_f32 v90, v16, v17
	v_cvt_pk_bf16_f32 v91, v18, v19
	ds_read2_b64 v[80:83], v224 offset0:16 offset1:20
	s_waitcnt lgkmcnt(8)
	v_mfma_f32_16x16x32_bf16 v[96:99], v[92:95], v[84:87], 0
	s_add_u32 s98, s98, 0x2000
	s_addc_u32 s99, s99, 0
	global_load_dword v247, v151, s[98:99]
	v_mfma_f32_16x16x32_bf16 v[92:95], v[92:95], v[88:91], 0
	ds_read2_b64 v[128:131], v225 offset0:16 offset1:20
	s_waitcnt lgkmcnt(8)
	v_mfma_f32_16x16x32_bf16 v[104:107], v[100:103], v[84:87], 0
	v_mfma_f32_16x16x32_bf16 v[100:103], v[100:103], v[88:91], 0
	ds_read2_b64 v[132:135], v226 offset0:16 offset1:20
	s_waitcnt lgkmcnt(8)
	v_mfma_f32_16x16x32_bf16 v[112:115], v[108:111], v[84:87], 0
	v_mfma_f32_16x16x32_bf16 v[108:111], v[108:111], v[88:91], 0
	ds_read2_b64 v[136:139], v227 offset0:16 offset1:20
	s_add_u32 s98, s98, 0x2000
	s_addc_u32 s99, s99, 0
	global_load_dword v246, v151, s[98:99]
	s_waitcnt lgkmcnt(8)
	v_mfma_f32_16x16x32_bf16 v[84:87], v[116:119], v[84:87], 0
	v_mfma_f32_16x16x32_bf16 v[88:91], v[116:119], v[88:91], 0
	v_cvt_pk_bf16_f32 v116, v20, v21
	v_cvt_pk_bf16_f32 v117, v22, v23
	v_cvt_pk_bf16_f32 v118, v28, v29
	v_cvt_pk_bf16_f32 v119, v30, v31
	v_cvt_pk_bf16_f32 v120, v24, v25
	v_cvt_pk_bf16_f32 v121, v26, v27
	v_cvt_pk_bf16_f32 v122, v32, v33
	s_add_u32 s98, s98, 0x2000
	s_addc_u32 s99, s99, 0
	global_load_dword v245, v151, s[98:99]
	v_cvt_pk_bf16_f32 v123, v34, v35
	ds_read2_b64 v[140:143], v224 offset0:24 offset1:28
	s_waitcnt lgkmcnt(8)
	v_mfma_f32_16x16x32_bf16 v[96:99], v[124:127], v[116:119], v[96:99]
	v_mfma_f32_16x16x32_bf16 v[92:95], v[124:127], v[120:123], v[92:95]
	ds_read2_b64 v[144:147], v225 offset0:24 offset1:28
	s_waitcnt lgkmcnt(8)
	v_mfma_f32_16x16x32_bf16 v[104:107], v[68:71], v[116:119], v[104:107]
	v_mfma_f32_16x16x32_bf16 v[100:103], v[68:71], v[120:123], v[100:103]
	s_waitcnt lgkmcnt(7)
	s_add_u32 s98, s98, 0x2000
	s_addc_u32 s99, s99, 0
	global_load_dword v244, v151, s[98:99]
	v_mfma_f32_16x16x32_bf16 v[112:115], v[72:75], v[116:119], v[112:115]
	v_mfma_f32_16x16x32_bf16 v[108:111], v[72:75], v[120:123], v[108:111]
	s_waitcnt lgkmcnt(6)
	v_mfma_f32_16x16x32_bf16 v[84:87], v[76:79], v[116:119], v[84:87]
	v_cvt_pk_bf16_f32 v116, v36, v37
	v_cvt_pk_bf16_f32 v117, v38, v39
	v_cvt_pk_bf16_f32 v118, v44, v45
	v_mfma_f32_16x16x32_bf16 v[88:91], v[76:79], v[120:123], v[88:91]
	v_cvt_pk_bf16_f32 v119, v46, v47
	v_cvt_pk_bf16_f32 v120, v40, v41
	s_add_u32 s98, s98, 0x2000
	s_addc_u32 s99, s99, 0
	global_load_dword v243, v151, s[98:99]
	v_cvt_pk_bf16_f32 v121, v42, v43
	v_cvt_pk_bf16_f32 v122, v48, v49
	v_cvt_pk_bf16_f32 v123, v50, v51
	s_waitcnt lgkmcnt(5)
	v_mfma_f32_16x16x32_bf16 v[96:99], v[80:83], v[116:119], v[96:99]
	v_mfma_f32_16x16x32_bf16 v[92:95], v[80:83], v[120:123], v[92:95]
	s_waitcnt lgkmcnt(4)
	v_mfma_f32_16x16x32_bf16 v[104:107], v[128:131], v[116:119], v[104:107]
	v_mfma_f32_16x16x32_bf16 v[100:103], v[128:131], v[120:123], v[100:103]
	s_waitcnt lgkmcnt(3)
	s_add_u32 s98, s98, 0x2000
	s_addc_u32 s99, s99, 0
	global_load_dword v242, v151, s[98:99]
	v_mfma_f32_16x16x32_bf16 v[112:115], v[132:135], v[116:119], v[112:115]
	v_mfma_f32_16x16x32_bf16 v[108:111], v[132:135], v[120:123], v[108:111]
	s_waitcnt lgkmcnt(2)
	v_mfma_f32_16x16x32_bf16 v[84:87], v[136:139], v[116:119], v[84:87]
	v_mfma_f32_16x16x32_bf16 v[116:119], v[136:139], v[120:123], v[88:91]
	s_nop 2
	v_cvt_pk_bf16_f32 v88, v52, v53
	v_cvt_pk_bf16_f32 v89, v54, v55
	v_cvt_pk_bf16_f32 v90, v60, v61
	v_cvt_pk_bf16_f32 v91, v62, v63
	s_add_u32 s98, s98, 0x2000
	s_addc_u32 s99, s99, 0
	global_load_dword v241, v151, s[98:99]
	v_cvt_pk_bf16_f32 v120, v56, v57
	v_cvt_pk_bf16_f32 v121, v58, v59
	v_cvt_pk_bf16_f32 v122, v64, v65
	v_cvt_pk_bf16_f32 v123, v66, v67
	s_waitcnt lgkmcnt(1)
	v_mfma_f32_16x16x32_bf16 v[128:131], v[140:143], v[88:91], v[96:99]
	v_mfma_f32_16x16x32_bf16 v[124:127], v[140:143], v[120:123], v[92:95]
	s_nop 2
	ds_read2_b64 v[92:95], v226 offset0:24 offset1:28
	s_nop 2
	s_add_u32 s98, s98, 0x2000
	s_addc_u32 s99, s99, 0
	global_load_dword v240, v151, s[98:99]
	s_waitcnt lgkmcnt(1)
	v_mfma_f32_16x16x32_bf16 v[104:107], v[144:147], v[88:91], v[104:107]
	v_mfma_f32_16x16x32_bf16 v[132:135], v[144:147], v[120:123], v[100:103]
	s_waitcnt lgkmcnt(0)
	v_mfma_f32_16x16x32_bf16 v[100:103], v[92:95], v[88:91], v[112:115]
	v_mfma_f32_16x16x32_bf16 v[96:99], v[92:95], v[120:123], v[108:111]
	ds_read2_b64 v[92:95], v227 offset0:24 offset1:28
	s_waitcnt lgkmcnt(0)
	v_mfma_f32_16x16x32_bf16 v[88:91], v[92:95], v[88:91], v[84:87]
	v_mfma_f32_16x16x32_bf16 v[92:95], v[92:95], v[120:123], v[116:119]
	s_add_u32 s98, s98, 0x2000
	s_addc_u32 s99, s99, 0
	global_load_dword v239, v151, s[98:99]
	v_add_u32_e32 v120, s33, v156
	s_nop 0
	ds_read_b128 v[84:87], v120
	ds_read_b128 v[68:71], v120 offset:64
	ds_read_b128 v[72:75], v120 offset:128
	s_nop 0
	s_waitcnt lgkmcnt(2)
	v_mul_f32_e32 v2, 0x3fb8aa3b, v84
	v_mul_f32_e32 v84, 0x3fb8aa3b, v86
	v_exp_f32_e32 v108, v84
	s_add_u32 s98, s98, 0x2000
	s_addc_u32 s99, s99, 0
	global_load_dword v238, v151, s[98:99]
	v_mul_f32_e32 v84, 0x3fb8aa3b, v87
	v_exp_f32_e32 v109, v84
	v_mul_f32_e32 v3, 0x3fb8aa3b, v85
	v_exp_f32_e32 v2, v2
	v_exp_f32_e32 v3, v3
	v_pk_mul_f32 v[86:87], v[130:131], v[108:109]
	v_pk_mul_f32 v[118:119], v[126:127], v[108:109]
	v_pk_mul_f32 v[84:85], v[128:129], v[2:3]
	v_pk_mul_f32 v[116:117], v[124:125], v[2:3]
	s_waitcnt lgkmcnt(1)
	s_add_u32 s98, s98, 0x2000
	s_addc_u32 s99, s99, 0
	global_load_dword v237, v151, s[98:99]
	v_mul_f32_e32 v2, 0x3fb8aa3b, v68
	v_mul_f32_e32 v108, 0x3fb8aa3b, v70
	v_mul_f32_e32 v3, 0x3fb8aa3b, v69
	v_exp_f32_e32 v112, v108
	v_mul_f32_e32 v108, 0x3fb8aa3b, v71
	v_exp_f32_e32 v2, v2
	v_exp_f32_e32 v3, v3
	v_exp_f32_e32 v113, v108
	v_pk_mul_f32 v[108:109], v[104:105], v[2:3]
	v_pk_mul_f32 v[110:111], v[106:107], v[112:113]
	s_add_u32 s98, s98, 0x2000
	s_addc_u32 s99, s99, 0
	global_load_dword v236, v151, s[98:99]
	v_pk_mul_f32 v[114:115], v[134:135], v[112:113]
	v_pk_mul_f32 v[112:113], v[132:133], v[2:3]
	s_waitcnt lgkmcnt(0)
	v_mul_f32_e32 v2, 0x3fb8aa3b, v72
	v_mul_f32_e32 v3, 0x3fb8aa3b, v73
	v_mul_f32_e32 v104, 0x3fb8aa3b, v74
	v_mul_f32_e32 v105, 0x3fb8aa3b, v75
	v_exp_f32_e32 v2, v2
	v_exp_f32_e32 v3, v3
	v_exp_f32_e32 v104, v104
	v_exp_f32_e32 v105, v105
	v_pk_mul_f32 v[100:101], v[100:101], v[2:3]
	v_pk_mul_f32 v[102:103], v[102:103], v[104:105]
	v_pk_mul_f32 v[106:107], v[98:99], v[104:105]
	v_pk_mul_f32 v[104:105], v[96:97], v[2:3]
	ds_read_b128 v[96:99], v120 offset:192
	s_waitcnt lgkmcnt(0)
	s_barrier
	s_cmp_lg_u64 s[6:7], 0
	s_cbranch_scc0 .Lprio35_a
	s_setprio 1
.Lprio35_a:
	v_mul_f32_e32 v2, 0x3fb8aa3b, v96
	v_mul_f32_e32 v3, 0x3fb8aa3b, v97
	v_mul_f32_e32 v96, 0x3fb8aa3b, v98
	v_mul_f32_e32 v97, 0x3fb8aa3b, v99
	v_exp_f32_e32 v2, v2
	v_exp_f32_e32 v3, v3
	v_exp_f32_e32 v96, v96
	v_exp_f32_e32 v97, v97
	v_pk_mul_f32 v[88:89], v[88:89], v[2:3]
	v_pk_mul_f32 v[90:91], v[90:91], v[96:97]
	v_pk_mul_f32 v[98:99], v[94:95], v[96:97]
	v_pk_mul_f32 v[96:97], v[92:93], v[2:3]
	v_mov_b32_e32 v2, s33
	ds_read_b32 v253, v2 offset:252
	ds_read_b128 v[148:151], v209
	ds_read_b128 v[140:143], v209 offset:16
	ds_read_b128 v[144:147], v201
	ds_read_b128 v[124:127], v201 offset:16
	ds_read_b128 v[120:123], v192 offset:53248
	s_waitcnt lgkmcnt(5)
	v_mul_f32_e32 v2, 0x3fb8aa3b, v253
	v_exp_f32_e32 v2, v2
	s_nop 0
	v_pk_mul_f32 v[6:7], v[6:7], v[2:3] op_sel_hi:[1,0]
	v_pk_mul_f32 v[4:5], v[4:5], v[2:3] op_sel_hi:[1,0]
	v_pk_mul_f32 v[74:75], v[10:11], v[2:3] op_sel_hi:[1,0]
	v_pk_mul_f32 v[72:73], v[8:9], v[2:3] op_sel_hi:[1,0]
	v_pk_mul_f32 v[10:11], v[14:15], v[2:3] op_sel_hi:[1,0]
	v_pk_mul_f32 v[8:9], v[12:13], v[2:3] op_sel_hi:[1,0]
	v_pk_mul_f32 v[18:19], v[18:19], v[2:3] op_sel_hi:[1,0]
	v_pk_mul_f32 v[16:17], v[16:17], v[2:3] op_sel_hi:[1,0]
	v_pk_mul_f32 v[14:15], v[22:23], v[2:3] op_sel_hi:[1,0]
	v_pk_mul_f32 v[12:13], v[20:21], v[2:3] op_sel_hi:[1,0]
	v_pk_mul_f32 v[26:27], v[26:27], v[2:3] op_sel_hi:[1,0]
	v_pk_mul_f32 v[24:25], v[24:25], v[2:3] op_sel_hi:[1,0]
	v_pk_mul_f32 v[22:23], v[30:31], v[2:3] op_sel_hi:[1,0]
	v_pk_mul_f32 v[20:21], v[28:29], v[2:3] op_sel_hi:[1,0]
	v_pk_mul_f32 v[34:35], v[34:35], v[2:3] op_sel_hi:[1,0]
	v_pk_mul_f32 v[32:33], v[32:33], v[2:3] op_sel_hi:[1,0]
	v_pk_mul_f32 v[30:31], v[38:39], v[2:3] op_sel_hi:[1,0]
	v_pk_mul_f32 v[28:29], v[36:37], v[2:3] op_sel_hi:[1,0]
	v_pk_mul_f32 v[42:43], v[42:43], v[2:3] op_sel_hi:[1,0]
	v_pk_mul_f32 v[40:41], v[40:41], v[2:3] op_sel_hi:[1,0]
	v_pk_mul_f32 v[38:39], v[46:47], v[2:3] op_sel_hi:[1,0]
	v_pk_mul_f32 v[36:37], v[44:45], v[2:3] op_sel_hi:[1,0]
	v_pk_mul_f32 v[50:51], v[50:51], v[2:3] op_sel_hi:[1,0]
	v_pk_mul_f32 v[48:49], v[48:49], v[2:3] op_sel_hi:[1,0]
	v_pk_mul_f32 v[46:47], v[54:55], v[2:3] op_sel_hi:[1,0]
	v_pk_mul_f32 v[44:45], v[52:53], v[2:3] op_sel_hi:[1,0]
	v_pk_mul_f32 v[58:59], v[58:59], v[2:3] op_sel_hi:[1,0]
	v_pk_mul_f32 v[56:57], v[56:57], v[2:3] op_sel_hi:[1,0]
	v_pk_mul_f32 v[54:55], v[62:63], v[2:3] op_sel_hi:[1,0]
	v_pk_mul_f32 v[52:53], v[60:61], v[2:3] op_sel_hi:[1,0]
	v_pk_mul_f32 v[62:63], v[66:67], v[2:3] op_sel_hi:[1,0]
	v_pk_mul_f32 v[60:61], v[64:65], v[2:3] op_sel_hi:[1,0]
	ds_read_b128 v[64:67], v192 offset:55552
	ds_read_b32 v2, v229
	ds_read_b128 v[68:71], v232
	ds_read_b128 v[76:79], v232 offset:16
	s_waitcnt lgkmcnt(2)
	v_sub_f32_e32 v3, v2, v148
	v_mul_f32_e32 v3, 0x3fb8aa3b, v3
	v_exp_f32_e32 v3, v3
	s_waitcnt lgkmcnt(1)
	v_mul_f32_e32 v3, v68, v3
	v_sub_f32_e32 v68, v2, v149
	v_mul_f32_e32 v68, 0x3fb8aa3b, v68
	v_exp_f32_e32 v68, v68
	v_mul_f32_e32 v3, v144, v3
	v_cndmask_b32_e64 v3, v3, 0, s[24:25]
	v_mul_f32_e32 v68, v69, v68
	v_sub_f32_e32 v69, v2, v150
	v_mul_f32_e32 v69, 0x3fb8aa3b, v69
	v_exp_f32_e32 v69, v69
	v_mul_f32_e32 v68, v145, v68
	v_cndmask_b32_e64 v68, 0, v68, s[26:27]
	ds_read_b32 v80, v229 offset:64
	ds_read_b128 v[128:131], v232 offset:4352
	ds_read_b128 v[132:135], v232 offset:4368
	v_cvt_pk_bf16_f32 v68, v3, v68
	v_mul_f32_e32 v69, v70, v69
	v_sub_f32_e32 v70, v2, v151
	v_mul_f32_e32 v70, 0x3fb8aa3b, v70
	v_exp_f32_e32 v70, v70
	v_mul_f32_e32 v69, v146, v69
	v_cndmask_b32_e64 v69, v69, 0, s[28:29]
	v_mul_f32_e32 v70, v71, v70
	v_sub_f32_e32 v71, v2, v140
	v_mul_f32_e32 v71, 0x3fb8aa3b, v71
	v_exp_f32_e32 v71, v71
	v_mul_f32_e32 v70, v147, v70
	v_cndmask_b32_e64 v70, v70, 0, s[30:31]
	v_cvt_pk_bf16_f32 v69, v69, v70
	s_waitcnt lgkmcnt(3)
	v_mul_f32_e32 v71, v76, v71
	v_sub_f32_e32 v76, v2, v141
	v_mul_f32_e32 v76, 0x3fb8aa3b, v76
	v_exp_f32_e32 v76, v76
	v_mul_f32_e32 v71, v124, v71
	v_cndmask_b32_e64 v71, v71, 0, s[34:35]
	v_mul_f32_e32 v76, v77, v76
	v_sub_f32_e32 v77, v2, v142
	v_sub_f32_e32 v2, v2, v143
	v_mul_f32_e32 v77, 0x3fb8aa3b, v77
	v_mul_f32_e32 v2, 0x3fb8aa3b, v2
	v_exp_f32_e32 v77, v77
	v_exp_f32_e32 v2, v2
	v_mul_f32_e32 v76, v125, v76
	v_cndmask_b32_e64 v76, v76, 0, s[36:37]
	v_mul_f32_e32 v77, v78, v77
	v_mul_f32_e32 v2, v79, v2
	v_mul_f32_e32 v77, v126, v77
	v_mul_f32_e32 v2, v127, v2
	v_cndmask_b32_e64 v77, v77, 0, s[38:39]
	v_cndmask_b32_e64 v2, v2, 0, s[40:41]
	v_cvt_pk_bf16_f32 v70, v71, v76
	v_cvt_pk_bf16_f32 v71, v77, v2
	s_nop 0
	s_nop 0
	v_mfma_f32_16x16x32_bf16 v[92:95], v[68:71], v[120:123], v[84:87]
	v_mfma_f32_16x16x32_bf16 v[84:87], v[68:71], v[64:67], v[116:119]
	s_waitcnt lgkmcnt(2)
	v_sub_f32_e32 v3, v80, v148
	v_mul_f32_e32 v3, 0x3fb8aa3b, v3
	v_exp_f32_e32 v3, v3
	s_waitcnt lgkmcnt(1)
	v_mul_f32_e32 v3, v128, v3
	v_sub_f32_e32 v68, v80, v149
	v_mul_f32_e32 v68, 0x3fb8aa3b, v68
	v_exp_f32_e32 v68, v68
	v_mul_f32_e32 v3, v144, v3
	v_cndmask_b32_e64 v3, v3, 0, s[42:43]
	v_mul_f32_e32 v68, v129, v68
	v_sub_f32_e32 v69, v80, v150
	v_mul_f32_e32 v69, 0x3fb8aa3b, v69
	v_exp_f32_e32 v69, v69
	v_mul_f32_e32 v68, v145, v68
	ds_read_b32 v116, v229 offset:128
	ds_read_b128 v[136:139], v232 offset:8704
	v_cndmask_b32_e64 v68, 0, v68, s[44:45]
	v_cvt_pk_bf16_f32 v68, v3, v68
	v_mul_f32_e32 v69, v130, v69
	v_sub_f32_e32 v70, v80, v151
	v_mul_f32_e32 v70, 0x3fb8aa3b, v70
	v_exp_f32_e32 v70, v70
	v_mul_f32_e32 v69, v146, v69
	v_cndmask_b32_e64 v69, v69, 0, s[46:47]
	v_mul_f32_e32 v70, v131, v70
	v_sub_f32_e32 v71, v80, v140
	v_mul_f32_e32 v71, 0x3fb8aa3b, v71
	v_exp_f32_e32 v71, v71
	v_mul_f32_e32 v70, v147, v70
	v_cndmask_b32_e64 v70, v70, 0, s[48:49]
	v_cvt_pk_bf16_f32 v69, v69, v70
	s_waitcnt lgkmcnt(2)
	v_mul_f32_e32 v71, v132, v71
	v_sub_f32_e32 v76, v80, v141
	v_mul_f32_e32 v76, 0x3fb8aa3b, v76
	v_exp_f32_e32 v76, v76
	v_mul_f32_e32 v71, v124, v71
	v_cndmask_b32_e64 v71, v71, 0, s[50:51]
	v_mul_f32_e32 v76, v133, v76
	v_sub_f32_e32 v77, v80, v142
	v_sub_f32_e32 v2, v80, v143
	v_mul_f32_e32 v77, 0x3fb8aa3b, v77
	v_mul_f32_e32 v2, 0x3fb8aa3b, v2
	v_exp_f32_e32 v77, v77
	v_exp_f32_e32 v2, v2
	v_mul_f32_e32 v76, v125, v76
	v_cndmask_b32_e64 v76, v76, 0, s[52:53]
	v_mul_f32_e32 v77, v134, v77
	v_mul_f32_e32 v2, v135, v2
	v_mul_f32_e32 v77, v126, v77
	v_mul_f32_e32 v2, v127, v2
	v_cndmask_b32_e64 v77, v77, 0, s[54:55]
	v_cndmask_b32_e64 v2, v2, 0, s[56:57]
	v_cvt_pk_bf16_f32 v70, v71, v76
	v_cvt_pk_bf16_f32 v71, v77, v2
	s_nop 0
	s_nop 0
	v_mfma_f32_16x16x32_bf16 v[76:79], v[68:71], v[120:123], v[108:111]
	s_nop 2
	ds_read_b128 v[108:111], v232 offset:8720
	s_nop 0
	s_waitcnt lgkmcnt(2)
	v_sub_f32_e32 v3, v116, v148
	v_mul_f32_e32 v3, 0x3fb8aa3b, v3
	v_exp_f32_e32 v3, v3
	v_mfma_f32_16x16x32_bf16 v[68:71], v[68:71], v[64:67], v[112:115]
	s_waitcnt lgkmcnt(1)
	v_mul_f32_e32 v3, v136, v3
	v_sub_f32_e32 v80, v116, v149
	v_mul_f32_e32 v80, 0x3fb8aa3b, v80
	v_exp_f32_e32 v80, v80
	ds_read_b32 v112, v229 offset:192
	ds_read_b128 v[128:131], v232 offset:13056
	v_mul_f32_e32 v3, v144, v3
	v_mul_f32_e32 v80, v137, v80
	v_sub_f32_e32 v81, v116, v150
	v_mul_f32_e32 v81, 0x3fb8aa3b, v81
	v_exp_f32_e32 v81, v81
	v_mul_f32_e32 v80, v145, v80
	v_cvt_pk_bf16_f32 v80, v3, v80
	v_mul_f32_e32 v81, v138, v81
	v_sub_f32_e32 v82, v116, v151
	v_mul_f32_e32 v82, 0x3fb8aa3b, v82
	v_exp_f32_e32 v82, v82
	v_mul_f32_e32 v81, v146, v81
	v_mul_f32_e32 v82, v139, v82
	v_sub_f32_e32 v83, v116, v140
	v_mul_f32_e32 v83, 0x3fb8aa3b, v83
	v_exp_f32_e32 v83, v83
	v_mul_f32_e32 v82, v147, v82
	v_cvt_pk_bf16_f32 v81, v81, v82
	s_waitcnt lgkmcnt(2)
	v_mul_f32_e32 v83, v108, v83
	v_sub_f32_e32 v108, v116, v141
	v_mul_f32_e32 v108, 0x3fb8aa3b, v108
	v_exp_f32_e32 v108, v108
	v_mul_f32_e32 v83, v124, v83
	v_mul_f32_e32 v108, v109, v108
	v_sub_f32_e32 v109, v116, v142
	v_sub_f32_e32 v2, v116, v143
	v_mul_f32_e32 v109, 0x3fb8aa3b, v109
	v_mul_f32_e32 v2, 0x3fb8aa3b, v2
	v_exp_f32_e32 v109, v109
	v_exp_f32_e32 v2, v2
	v_mul_f32_e32 v108, v125, v108
	v_cvt_pk_bf16_f32 v82, v83, v108
	v_mul_f32_e32 v109, v110, v109
	v_mul_f32_e32 v2, v111, v2
	v_mul_f32_e32 v109, v126, v109
	v_mul_f32_e32 v2, v127, v2
	v_cvt_pk_bf16_f32 v83, v109, v2
	s_nop 0
	s_nop 0
	v_mfma_f32_16x16x32_bf16 v[132:135], v[80:83], v[120:123], v[100:103]
	s_nop 2
	ds_read_b128 v[100:103], v232 offset:13072
	v_mfma_f32_16x16x32_bf16 v[136:139], v[80:83], v[64:67], v[104:107]
	s_waitcnt lgkmcnt(2)
	v_sub_f32_e32 v3, v112, v148
	v_mul_f32_e32 v3, 0x3fb8aa3b, v3
	v_exp_f32_e32 v3, v3
	s_waitcnt lgkmcnt(1)
	v_mul_f32_e32 v3, v128, v3
	v_sub_f32_e32 v80, v112, v149
	v_mul_f32_e32 v80, 0x3fb8aa3b, v80
	v_exp_f32_e32 v80, v80
	v_mul_f32_e32 v3, v144, v3
	v_mul_f32_e32 v80, v129, v80
	v_sub_f32_e32 v81, v112, v150
	v_mul_f32_e32 v81, 0x3fb8aa3b, v81
	v_exp_f32_e32 v81, v81
	v_mul_f32_e32 v80, v145, v80
	v_mul_f32_e32 v81, v130, v81
	v_sub_f32_e32 v82, v112, v151
	v_mul_f32_e32 v82, 0x3fb8aa3b, v82
	v_exp_f32_e32 v82, v82
	v_mul_f32_e32 v81, v146, v81
	v_mul_f32_e32 v82, v131, v82
	v_sub_f32_e32 v83, v112, v140
	v_mul_f32_e32 v83, 0x3fb8aa3b, v83
	v_exp_f32_e32 v83, v83
	v_mul_f32_e32 v82, v147, v82
	s_waitcnt lgkmcnt(0)
	v_mul_f32_e32 v83, v100, v83
	v_sub_f32_e32 v100, v112, v141
	v_mul_f32_e32 v100, 0x3fb8aa3b, v100
	v_exp_f32_e32 v100, v100
	v_mul_f32_e32 v83, v124, v83
	v_mul_f32_e32 v100, v101, v100
	v_mul_f32_e32 v104, v125, v100
	v_sub_f32_e32 v100, v112, v142
	v_sub_f32_e32 v2, v112, v143
	v_mul_f32_e32 v100, 0x3fb8aa3b, v100
	v_mul_f32_e32 v2, 0x3fb8aa3b, v2
	v_exp_f32_e32 v100, v100
	v_exp_f32_e32 v2, v2
	v_mul_f32_e32 v100, v102, v100
	v_mul_f32_e32 v2, v103, v2
	v_mul_f32_e32 v105, v126, v100
	v_mul_f32_e32 v2, v127, v2
	v_cvt_pk_bf16_f32 v100, v3, v80
	v_cvt_pk_bf16_f32 v101, v81, v82
	v_cvt_pk_bf16_f32 v102, v83, v104
	v_cvt_pk_bf16_f32 v103, v105, v2
	v_sub_f32_e32 v2, v253, v148
	s_nop 0
	v_mfma_f32_16x16x32_bf16 v[80:83], v[100:103], v[120:123], v[88:91]
	v_sub_f32_e32 v3, v253, v149
	v_mul_f32_e32 v2, 0x3fb8aa3b, v2
	v_mul_f32_e32 v3, 0x3fb8aa3b, v3
	v_sub_f32_e32 v88, v253, v150
	v_mul_f32_e32 v88, 0x3fb8aa3b, v88
	v_exp_f32_e32 v88, v88
	v_mfma_f32_16x16x32_bf16 v[128:131], v[100:103], v[64:67], v[96:99]
	v_exp_f32_e32 v2, v2
	v_exp_f32_e32 v3, v3
	v_and_b32_e32 v89, 0xffff0000, v120
	v_mul_f32_e32 v96, v146, v88
	v_sub_f32_e32 v88, v253, v151
	v_mul_f32_e32 v88, 0x3fb8aa3b, v88
	v_exp_f32_e32 v88, v88
	v_mul_f32_e32 v2, v144, v2
	v_mul_f32_e32 v3, v145, v3
	v_lshlrev_b32_e32 v90, 16, v121
	v_mul_f32_e32 v97, v147, v88
	v_sub_f32_e32 v88, v253, v140
	v_mul_f32_e32 v88, 0x3fb8aa3b, v88
	v_exp_f32_e32 v88, v88
	v_lshlrev_b32_e32 v102, 16, v122
	v_mul_f32_e32 v89, v3, v89
	v_mul_f32_e32 v90, v96, v90
	v_mul_f32_e32 v98, v124, v88
	v_sub_f32_e32 v88, v253, v141
	v_mul_f32_e32 v88, 0x3fb8aa3b, v88
	v_exp_f32_e32 v88, v88
	v_and_b32_e32 v91, 0xffff0000, v121
	v_mul_f32_e32 v102, v98, v102
	v_and_b32_e32 v103, 0xffff0000, v122
	v_mul_f32_e32 v99, v125, v88
	ds_read_b128 v[106:109], v233 offset:34816
	v_sub_f32_e32 v88, v253, v142
	v_mul_f32_e32 v88, 0x3fb8aa3b, v88
	ds_read_b128 v[110:113], v233 offset:37120
	v_exp_f32_e32 v88, v88
	v_mul_f32_e32 v91, v97, v91
	ds_read_b128 v[114:117], v233 offset:39424
	v_mul_f32_e32 v103, v99, v103
	v_lshlrev_b32_e32 v104, 16, v123
	ds_read_b128 v[144:147], v233 offset:41728
	v_mul_f32_e32 v100, v126, v88
	v_sub_f32_e32 v88, v253, v143
	ds_read_b128 v[148:151], v233 offset:44032
	v_mul_f32_e32 v88, 0x3fb8aa3b, v88
	v_exp_f32_e32 v88, v88
	v_and_b32_e32 v105, 0xffff0000, v123
	v_mul_f32_e32 v104, v100, v104
	v_mul_f32_e32 v101, v127, v88
	v_lshlrev_b32_e32 v88, 16, v120
	v_mul_f32_e32 v88, v2, v88
	v_cvt_pk_bf16_f32 v88, v88, v89
	v_cvt_pk_bf16_f32 v89, v90, v91
	v_cvt_pk_bf16_f32 v90, v102, v103
	v_lshlrev_b32_e32 v102, 16, v64
	v_and_b32_e32 v64, 0xffff0000, v64
	v_mul_f32_e32 v3, v3, v64
	v_lshlrev_b32_e32 v64, 16, v65
	v_mul_f32_e32 v64, v96, v64
	v_lshlrev_b32_e32 v96, 16, v66
	v_and_b32_e32 v65, 0xffff0000, v65
	v_mul_f32_e32 v98, v98, v96
	v_and_b32_e32 v66, 0xffff0000, v66
	v_lshlrev_b32_e32 v96, 16, v67
	v_and_b32_e32 v67, 0xffff0000, v67
	v_mul_f32_e32 v65, v97, v65
	v_mul_f32_e32 v66, v99, v66
	v_mul_f32_e32 v99, v100, v96
	v_mul_f32_e32 v67, v101, v67
	v_mul_f32_e32 v105, v101, v105
	v_cvt_pk_bf16_f32 v91, v104, v105
	v_mul_f32_e32 v2, v2, v102
	v_cvt_pk_bf16_f32 v96, v2, v3
	v_cvt_pk_bf16_f32 v97, v64, v65
	v_cvt_pk_bf16_f32 v98, v98, v66
	v_cvt_pk_bf16_f32 v99, v99, v67
	s_waitcnt lgkmcnt(4)
	s_setprio 0
	v_mfma_f32_16x16x32_bf16 v[2:5], v[106:109], v[88:91], v[4:7]
	v_mfma_f32_16x16x32_bf16 v[140:143], v[106:109], v[96:99], v[72:75]
	s_waitcnt lgkmcnt(3)
	v_mfma_f32_16x16x32_bf16 v[120:123], v[110:113], v[88:91], v[8:11]
	s_nop 2
	ds_read_b128 v[6:9], v233 offset:46336
	s_nop 2
	s_waitcnt lgkmcnt(3)
	v_mfma_f32_16x16x32_bf16 v[124:127], v[114:117], v[88:91], v[12:15]
	v_mfma_f32_16x16x32_bf16 v[24:27], v[114:117], v[96:99], v[24:27]
	s_waitcnt lgkmcnt(2)
	v_mfma_f32_16x16x32_bf16 v[116:119], v[144:147], v[88:91], v[20:23]
	v_mfma_f32_16x16x32_bf16 v[32:35], v[144:147], v[96:99], v[32:35]
	v_mfma_f32_16x16x32_bf16 v[16:19], v[110:113], v[96:99], v[16:19]
	s_waitcnt lgkmcnt(1)
	v_mfma_f32_16x16x32_bf16 v[64:67], v[148:151], v[88:91], v[28:31]
	v_mfma_f32_16x16x32_bf16 v[40:43], v[148:151], v[96:99], v[40:43]
	s_waitcnt lgkmcnt(0)
	v_mfma_f32_16x16x32_bf16 v[100:103], v[6:9], v[88:91], v[36:39]
	v_mfma_f32_16x16x32_bf16 v[48:51], v[6:9], v[96:99], v[48:51]
	ds_read_b128 v[6:9], v233 offset:48640
	s_waitcnt lgkmcnt(0)
	v_mfma_f32_16x16x32_bf16 v[104:107], v[6:9], v[88:91], v[44:47]
	v_mfma_f32_16x16x32_bf16 v[56:59], v[6:9], v[96:99], v[56:59]
	ds_read_b128 v[6:9], v233 offset:50944
	s_nop 0
	ds_read_b128 v[44:47], v209 offset:128
	ds_read_b128 v[28:31], v209 offset:144
	ds_read_b128 v[36:39], v201 offset:128
	ds_read_b128 v[20:23], v201 offset:144
	ds_read_b128 v[10:13], v192 offset:53312
	s_waitcnt lgkmcnt(5)
	v_mfma_f32_16x16x32_bf16 v[108:111], v[6:9], v[88:91], v[52:55]
	v_mfma_f32_16x16x32_bf16 v[112:115], v[6:9], v[96:99], v[60:63]
	ds_read_b128 v[6:9], v192 offset:55616
	ds_read_b32 v14, v229 offset:128
	ds_read_b128 v[52:55], v232 offset:8832
	ds_read_b128 v[60:63], v232 offset:8848
	s_waitcnt lgkmcnt(2)
	v_sub_f32_e32 v15, v14, v44
	v_mul_f32_e32 v15, 0x3fb8aa3b, v15
	v_exp_f32_e32 v15, v15
	s_waitcnt lgkmcnt(1)
	v_mul_f32_e32 v15, v52, v15
	v_sub_f32_e32 v52, v14, v45
	v_mul_f32_e32 v52, 0x3fb8aa3b, v52
	v_exp_f32_e32 v52, v52
	v_mul_f32_e32 v15, v36, v15
	v_cndmask_b32_e64 v15, v15, 0, s[24:25]
	v_mul_f32_e32 v52, v53, v52
	v_sub_f32_e32 v53, v14, v46
	v_mul_f32_e32 v53, 0x3fb8aa3b, v53
	v_exp_f32_e32 v53, v53
	v_mul_f32_e32 v52, v37, v52
	v_cndmask_b32_e64 v52, v52, 0, s[58:59]
	ds_read_b32 v72, v229 offset:192
	ds_read_b128 v[144:147], v232 offset:13184
	ds_read_b128 v[148:151], v232 offset:13200
	v_cvt_pk_bf16_f32 v52, v15, v52
	v_mul_f32_e32 v53, v54, v53
	v_sub_f32_e32 v54, v14, v47
	v_mul_f32_e32 v54, 0x3fb8aa3b, v54
	v_exp_f32_e32 v54, v54
	v_mul_f32_e32 v53, v38, v53
	v_cndmask_b32_e64 v53, v53, 0, s[60:61]
	v_mul_f32_e32 v54, v55, v54
	v_sub_f32_e32 v55, v14, v28
	v_mul_f32_e32 v55, 0x3fb8aa3b, v55
	v_exp_f32_e32 v55, v55
	v_mul_f32_e32 v54, v39, v54
	v_cndmask_b32_e64 v54, v54, 0, s[62:63]
	v_cvt_pk_bf16_f32 v53, v53, v54
	s_waitcnt lgkmcnt(3)
	v_mul_f32_e32 v55, v60, v55
	v_sub_f32_e32 v60, v14, v29
	v_mul_f32_e32 v60, 0x3fb8aa3b, v60
	v_exp_f32_e32 v60, v60
	v_mul_f32_e32 v55, v20, v55
	v_cndmask_b32_e64 v55, v55, 0, s[64:65]
	v_mul_f32_e32 v60, v61, v60
	v_sub_f32_e32 v61, v14, v30
	v_sub_f32_e32 v14, v14, v31
	v_mul_f32_e32 v61, 0x3fb8aa3b, v61
	v_mul_f32_e32 v14, 0x3fb8aa3b, v14
	v_exp_f32_e32 v61, v61
	v_exp_f32_e32 v14, v14
	v_mul_f32_e32 v60, v21, v60
	v_cndmask_b32_e64 v60, v60, 0, s[66:67]
	v_mul_f32_e32 v61, v62, v61
	v_mul_f32_e32 v14, v63, v14
	v_mul_f32_e32 v61, v22, v61
	v_mul_f32_e32 v14, v23, v14
	v_cndmask_b32_e64 v61, v61, 0, s[68:69]
	v_cndmask_b32_e64 v14, v14, 0, s[70:71]
	v_cvt_pk_bf16_f32 v54, v55, v60
	v_cvt_pk_bf16_f32 v55, v61, v14
	s_nop 0
	s_nop 0
	v_mfma_f32_16x16x32_bf16 v[96:99], v[52:55], v[10:13], v[132:135]
	v_mfma_f32_16x16x32_bf16 v[88:91], v[52:55], v[6:9], v[136:139]
	s_waitcnt lgkmcnt(2)
	v_sub_f32_e32 v15, v72, v44
	v_mul_f32_e32 v15, 0x3fb8aa3b, v15
	v_exp_f32_e32 v15, v15
	s_waitcnt lgkmcnt(1)
	v_mul_f32_e32 v15, v144, v15
	v_sub_f32_e32 v52, v72, v45
	v_mul_f32_e32 v52, 0x3fb8aa3b, v52
	v_exp_f32_e32 v52, v52
	v_mul_f32_e32 v15, v36, v15
	v_cndmask_b32_e64 v15, v15, 0, s[72:73]
	v_mul_f32_e32 v52, v145, v52
	v_sub_f32_e32 v53, v72, v46
	v_mul_f32_e32 v53, 0x3fb8aa3b, v53
	v_exp_f32_e32 v53, v53
	v_mul_f32_e32 v52, v37, v52
	v_cndmask_b32_e64 v52, v52, 0, s[74:75]
	v_cvt_pk_bf16_f32 v52, v15, v52
	v_mul_f32_e32 v53, v146, v53
	v_sub_f32_e32 v54, v72, v47
	v_mul_f32_e32 v54, 0x3fb8aa3b, v54
	v_exp_f32_e32 v54, v54
	v_mul_f32_e32 v53, v38, v53
	v_cndmask_b32_e64 v53, v53, 0, s[76:77]
	v_sub_f32_e32 v15, v253, v45
	v_mul_f32_e32 v54, v147, v54
	v_sub_f32_e32 v55, v72, v28
	v_mul_f32_e32 v55, 0x3fb8aa3b, v55
	v_exp_f32_e32 v55, v55
	v_sub_f32_e32 v28, v253, v28
	v_mul_f32_e32 v28, 0x3fb8aa3b, v28
	v_exp_f32_e32 v28, v28
	s_waitcnt lgkmcnt(0)
	v_mul_f32_e32 v55, v148, v55
	v_sub_f32_e32 v60, v72, v29
	v_mul_f32_e32 v60, 0x3fb8aa3b, v60
	v_exp_f32_e32 v60, v60
	v_mul_f32_e32 v55, v20, v55
	v_mul_f32_e32 v20, v20, v28
	v_sub_f32_e32 v28, v253, v29
	v_mul_f32_e32 v60, v149, v60
	v_sub_f32_e32 v61, v72, v30
	v_sub_f32_e32 v14, v72, v31
	v_mul_f32_e32 v14, 0x3fb8aa3b, v14
	v_mul_f32_e32 v61, 0x3fb8aa3b, v61
	v_exp_f32_e32 v14, v14
	v_exp_f32_e32 v61, v61
	v_mul_f32_e32 v28, 0x3fb8aa3b, v28
	v_exp_f32_e32 v28, v28
	v_mul_f32_e32 v14, v151, v14
	v_mul_f32_e32 v54, v39, v54
	v_mul_f32_e32 v61, v150, v61
	v_mul_f32_e32 v14, v23, v14
	v_cndmask_b32_e64 v54, v54, 0, s[78:79]
	v_cndmask_b32_e64 v55, v55, 0, s[80:81]
	v_mul_f32_e32 v60, v21, v60
	v_mul_f32_e32 v61, v22, v61
	v_cndmask_b32_e64 v14, v14, 0, s[86:87]
	v_mul_f32_e32 v21, v21, v28
	v_sub_f32_e32 v28, v253, v30
	v_cndmask_b32_e64 v60, v60, 0, s[82:83]
	v_cndmask_b32_e64 v61, v61, 0, s[84:85]
	v_cvt_pk_bf16_f32 v53, v53, v54
	v_cvt_pk_bf16_f32 v54, v55, v60
	v_cvt_pk_bf16_f32 v55, v61, v14
	v_sub_f32_e32 v14, v253, v44
	v_mul_f32_e32 v15, 0x3fb8aa3b, v15
	v_mul_f32_e32 v28, 0x3fb8aa3b, v28
	v_mul_f32_e32 v14, 0x3fb8aa3b, v14
	v_exp_f32_e32 v15, v15
	v_exp_f32_e32 v28, v28
	v_exp_f32_e32 v14, v14
	v_mfma_f32_16x16x32_bf16 v[80:83], v[52:55], v[10:13], v[80:83]
	v_mul_f32_e32 v15, v37, v15
	v_sub_f32_e32 v37, v253, v47
	v_mul_f32_e32 v22, v22, v28
	v_sub_f32_e32 v28, v253, v31
	v_mul_f32_e32 v14, v36, v14
	v_sub_f32_e32 v36, v253, v46
	v_mul_f32_e32 v37, 0x3fb8aa3b, v37
	v_mul_f32_e32 v28, 0x3fb8aa3b, v28
	v_mul_f32_e32 v36, 0x3fb8aa3b, v36
	v_exp_f32_e32 v37, v37
	v_exp_f32_e32 v28, v28
	v_exp_f32_e32 v36, v36
	v_lshlrev_b32_e32 v29, 16, v11
	v_mul_f32_e32 v37, v39, v37
	v_mul_f32_e32 v23, v23, v28
	v_lshlrev_b32_e32 v28, 16, v10
	ds_read_b128 v[132:135], v233 offset:34880
	ds_read_b128 v[136:139], v233 offset:37184
	ds_read_b128 v[144:147], v233 offset:39488
	ds_read_b128 v[148:151], v233 offset:41792
	ds_read_b128 v[44:47], v233 offset:44096
	v_and_b32_e32 v10, 0xffff0000, v10
	v_and_b32_e32 v11, 0xffff0000, v11
	v_lshlrev_b32_e32 v30, 16, v12
	v_and_b32_e32 v12, 0xffff0000, v12
	v_lshlrev_b32_e32 v31, 16, v13
	v_and_b32_e32 v13, 0xffff0000, v13
	v_mul_f32_e32 v36, v38, v36
	v_mul_f32_e32 v10, v15, v10
	v_mul_f32_e32 v11, v37, v11
	v_mul_f32_e32 v12, v21, v12
	v_mul_f32_e32 v13, v23, v13
	v_mfma_f32_16x16x32_bf16 v[72:75], v[52:55], v[6:9], v[128:131]
	ds_read_b128 v[52:55], v233 offset:46400
	v_mul_f32_e32 v28, v14, v28
	v_mul_f32_e32 v29, v36, v29
	v_mul_f32_e32 v30, v20, v30
	v_mul_f32_e32 v31, v22, v31
	v_cvt_pk_bf16_f32 v60, v28, v10
	v_cvt_pk_bf16_f32 v61, v29, v11
	v_cvt_pk_bf16_f32 v62, v30, v12
	v_cvt_pk_bf16_f32 v63, v31, v13
	v_lshlrev_b32_e32 v10, 16, v6
	v_lshlrev_b32_e32 v11, 16, v7
	v_lshlrev_b32_e32 v12, 16, v8
	v_and_b32_e32 v8, 0xffff0000, v8
	v_lshlrev_b32_e32 v13, 16, v9
	v_and_b32_e32 v9, 0xffff0000, v9
	v_mul_f32_e32 v10, v14, v10
	v_and_b32_e32 v6, 0xffff0000, v6
	v_mul_f32_e32 v11, v36, v11
	v_and_b32_e32 v7, 0xffff0000, v7
	v_mul_f32_e32 v8, v21, v8
	v_mul_f32_e32 v9, v23, v9
	v_mul_f32_e32 v6, v15, v6
	v_mul_f32_e32 v7, v37, v7
	v_mul_f32_e32 v12, v20, v12
	v_mul_f32_e32 v13, v22, v13
	v_cvt_pk_bf16_f32 v128, v10, v6
	v_cvt_pk_bf16_f32 v129, v11, v7
	v_cvt_pk_bf16_f32 v130, v12, v8
	v_cvt_pk_bf16_f32 v131, v13, v9
	s_waitcnt lgkmcnt(4)
	v_mfma_f32_16x16x32_bf16 v[12:15], v[136:139], v[60:63], v[120:123]
	v_mfma_f32_16x16x32_bf16 v[16:19], v[136:139], v[128:131], v[16:19]
	s_waitcnt lgkmcnt(3)
	v_mfma_f32_16x16x32_bf16 v[20:23], v[144:147], v[60:63], v[124:127]
	v_mfma_f32_16x16x32_bf16 v[24:27], v[144:147], v[128:131], v[24:27]
	s_waitcnt lgkmcnt(2)
	v_mfma_f32_16x16x32_bf16 v[28:31], v[148:151], v[60:63], v[116:119]
	v_mfma_f32_16x16x32_bf16 v[32:35], v[148:151], v[128:131], v[32:35]
	s_waitcnt lgkmcnt(1)
	v_mfma_f32_16x16x32_bf16 v[36:39], v[44:47], v[60:63], v[64:67]
	s_nop 2
	ds_read_b128 v[64:67], v233 offset:48704
	s_nop 2
	v_mfma_f32_16x16x32_bf16 v[4:7], v[132:135], v[60:63], v[2:5]
	s_nop 2
	ds_read_b64 v[2:3], v234 offset:53248
	ds_read_u16 v192, v235
	v_mfma_f32_16x16x32_bf16 v[40:43], v[44:47], v[128:131], v[40:43]
	s_nop 1
	s_waitcnt lgkmcnt(3)
	v_mfma_f32_16x16x32_bf16 v[44:47], v[52:55], v[60:63], v[100:103]
	s_nop 2
	ds_read_u16 v103, v235 offset:528
	v_mfma_f32_16x16x32_bf16 v[48:51], v[52:55], v[128:131], v[48:51]
	s_nop 1
	s_waitcnt lgkmcnt(2)
	v_lshlrev_b32_e32 v100, 16, v2
	v_mfma_f32_16x16x32_bf16 v[52:55], v[64:67], v[60:63], v[104:107]
	v_and_b32_e32 v101, 0xffff0000, v2
	s_waitcnt lgkmcnt(1)
	v_lshlrev_b32_e32 v102, 16, v192
	s_waitcnt lgkmcnt(0)
	v_lshlrev_b32_e32 v103, 16, v103
	v_mfma_f32_16x16x32_bf16 v[56:59], v[64:67], v[128:131], v[56:59]
	ds_read_b128 v[64:67], v233 offset:51008
	ds_read_u16 v116, v235 offset:1056
	ds_read_u16 v117, v235 offset:1584
	ds_read_b64 v[104:105], v234 offset:55552
	ds_read_u16 v106, v235 offset:32
	ds_read_u16 v107, v235 offset:560
	v_pk_fma_f32 v[92:93], v[154:155], v[100:101], v[92:93]
	v_pk_mul_f32 v[100:101], v[102:103], s[96:97] op_sel_hi:[1,0]
	v_lshlrev_b32_e32 v2, 16, v3
	v_exp_f32_e32 v100, v100
	v_exp_f32_e32 v101, v101
	v_and_b32_e32 v3, 0xffff0000, v3
	v_pk_fma_f32 v[2:3], v[154:155], v[2:3], v[94:95]
	v_mfma_f32_16x16x32_bf16 v[8:11], v[132:135], v[128:131], v[140:143]
	v_add_f32_e64 v100, v100, 1.0
	v_add_f32_e64 v101, v101, 1.0
	v_rcp_f32_e32 v100, v100
	v_rcp_f32_e32 v101, v101
	s_waitcnt lgkmcnt(5)
	v_mfma_f32_16x16x32_bf16 v[60:63], v[64:67], v[60:63], v[108:111]
	v_mul_f32_e64 v100, v100, v102
	v_mul_f32_e64 v101, v101, v103
	v_pk_mul_f32 v[92:93], v[92:93], v[100:101]
	v_mfma_f32_16x16x32_bf16 v[64:67], v[64:67], v[128:131], v[112:115]
	v_cvt_pk_bf16_f32 v102, v92, v93
	ds_write_b16 v235, v102
	ds_write_b16_d16_hi v235, v102 offset:528
	s_waitcnt lgkmcnt(6)
	v_lshlrev_b32_e32 v92, 16, v116
	s_waitcnt lgkmcnt(5)
	v_lshlrev_b32_e32 v93, 16, v117
	ds_read_u16 v108, v235 offset:1088
	ds_read_u16 v109, v235 offset:1616
	v_pk_mul_f32 v[94:95], v[92:93], s[96:97] op_sel_hi:[1,0]
	s_nop 0
	v_exp_f32_e32 v94, v94
	v_exp_f32_e32 v95, v95
	s_nop 0
	v_pk_add_f32 v[94:95], v[94:95], 1.0 op_sel_hi:[1,0]
	s_nop 0
	v_rcp_f32_e32 v94, v94
	v_rcp_f32_e32 v95, v95
	s_nop 0
	v_pk_mul_f32 v[92:93], v[94:95], v[92:93]
	s_nop 0
	v_pk_mul_f32 v[2:3], v[2:3], v[92:93]
	s_nop 0
	v_cvt_pk_bf16_f32 v103, v2, v3
	ds_write_b16 v235, v103 offset:1056
	ds_write_b16_d16_hi v235, v103 offset:1584
	s_waitcnt lgkmcnt(8)
	v_lshlrev_b32_e32 v92, 16, v104
	v_and_b32_e32 v93, 0xffff0000, v104
	s_waitcnt lgkmcnt(7)
	v_lshlrev_b32_e32 v94, 16, v106
	s_waitcnt lgkmcnt(6)
	v_lshlrev_b32_e32 v95, 16, v107
	v_pk_fma_f32 v[84:85], v[154:155], v[92:93], v[84:85]
	v_pk_mul_f32 v[92:93], v[94:95], s[96:97] op_sel_hi:[1,0]
	v_lshlrev_b32_e32 v2, 16, v105
	v_exp_f32_e32 v92, v92
	v_exp_f32_e32 v93, v93
	v_and_b32_e32 v3, 0xffff0000, v105
	v_pk_fma_f32 v[2:3], v[154:155], v[2:3], v[86:87]
	v_pk_add_f32 v[92:93], v[92:93], 1.0 op_sel_hi:[1,0]
	s_nop 0
	v_rcp_f32_e32 v92, v92
	v_rcp_f32_e32 v93, v93
	s_nop 0
	v_pk_mul_f32 v[92:93], v[92:93], v[94:95]
	s_nop 0
	v_pk_mul_f32 v[84:85], v[84:85], v[92:93]
	s_nop 0
	v_cvt_pk_bf16_f32 v92, v84, v85
	ds_write_b16 v235, v92 offset:32
	ds_write_b16_d16_hi v235, v92 offset:560
	s_waitcnt lgkmcnt(5)
	v_lshlrev_b32_e32 v84, 16, v108
	s_waitcnt lgkmcnt(4)
	v_lshlrev_b32_e32 v85, 16, v109
	v_pk_mul_f32 v[86:87], v[84:85], s[96:97] op_sel_hi:[1,0]
	s_nop 0
	v_exp_f32_e32 v86, v86
	v_exp_f32_e32 v87, v87
	s_nop 0
	v_pk_add_f32 v[86:87], v[86:87], 1.0 op_sel_hi:[1,0]
	s_nop 0
	v_rcp_f32_e32 v86, v86
	v_rcp_f32_e32 v87, v87
	s_nop 0
	v_pk_mul_f32 v[84:85], v[86:87], v[84:85]
	s_nop 0
	v_pk_mul_f32 v[2:3], v[2:3], v[84:85]
	v_lshlrev_b32_e32 v84, 16, v92
	v_cvt_pk_bf16_f32 v93, v2, v3
	ds_write_b16 v235, v93 offset:1088
	ds_write_b16_d16_hi v235, v93 offset:1616
	v_and_b32_e32 v85, 0xffff0000, v92
	v_lshlrev_b32_e32 v92, 16, v93
	v_and_b32_e32 v93, 0xffff0000, v93
	v_pk_mul_f32 v[84:85], v[84:85], v[84:85]
	v_and_b32_e32 v3, 0xffff0000, v102
	v_lshlrev_b32_e32 v86, 16, v103
	v_lshlrev_b32_e32 v2, 16, v102
	v_and_b32_e32 v87, 0xffff0000, v103
	v_pk_mul_f32 v[92:93], v[92:93], v[92:93]
	v_pk_fma_f32 v[2:3], v[2:3], v[2:3], v[84:85]
	v_pk_fma_f32 v[86:87], v[86:87], v[86:87], v[92:93]
	s_nop 0
	v_add_u32_e32 v102, s12, v156
	v_add_f32_dpp v2, v2, v2 quad_perm:[1,0,3,2] row_mask:0xf bank_mask:0xf
	v_add_f32_dpp v3, v3, v3 quad_perm:[1,0,3,2] row_mask:0xf bank_mask:0xf
	v_add_f32_dpp v86, v86, v86 quad_perm:[1,0,3,2] row_mask:0xf bank_mask:0xf
	v_add_f32_dpp v87, v87, v87 quad_perm:[1,0,3,2] row_mask:0xf bank_mask:0xf
	v_add_f32_dpp v2, v2, v2 quad_perm:[2,3,0,1] row_mask:0xf bank_mask:0xf
	v_add_f32_dpp v3, v3, v3 quad_perm:[2,3,0,1] row_mask:0xf bank_mask:0xf
	v_add_f32_dpp v86, v86, v86 quad_perm:[2,3,0,1] row_mask:0xf bank_mask:0xf
	v_add_f32_dpp v87, v87, v87 quad_perm:[2,3,0,1] row_mask:0xf bank_mask:0xf
	v_add_f32_dpp v2, v2, v2 row_half_mirror row_mask:0xf bank_mask:0xf
	v_add_f32_dpp v3, v3, v3 row_half_mirror row_mask:0xf bank_mask:0xf
	v_add_f32_dpp v86, v86, v86 row_half_mirror row_mask:0xf bank_mask:0xf
	v_add_f32_dpp v87, v87, v87 row_half_mirror row_mask:0xf bank_mask:0xf
	v_add_f32_dpp v84, v2, v2 row_mirror row_mask:0xf bank_mask:0xf
	v_add_f32_dpp v85, v3, v3 row_mirror row_mask:0xf bank_mask:0xf
	v_add_f32_dpp v86, v86, v86 row_mirror row_mask:0xf bank_mask:0xf
	v_add_f32_dpp v87, v87, v87 row_mirror row_mask:0xf bank_mask:0xf
	s_and_saveexec_b64 s[94:95], s[10:11]
	s_cbranch_execz .LBB0_382
	ds_write_b128 v102, v[84:87]
